# scan_unit loop: 32 loads in flight (was one load per step waited immediately), same arithmetic and store order; on top of drain-free epilogues
# speedup vs baseline: 1.0115x; 1.0115x over previous
; __device__ __forceinline__ unsigned pk2(float lo, float hi) { return pg8::cvt_pk_bf16(lo, hi); }
; __device__ __forceinline__ float ret_log2gamma(int h) { return log2f(1.f - exp2f(-5.f - (float)h)); }
; __device__ __forceinline__ void st_sc1_u2(void* p, unsigned lo, unsigned hi) { __hip_atomic_store((GAS unsigned long long*)p, ((unsigned long long)hi << 32) | (unsigned long long)lo, __ATOMIC_RELAXED, __HIP_MEMORY_SCOPE_AGENT); }
; __device__ __forceinline__ void scan_unit(const float* KVT, bfu* RT, int s) {
;     int tid = threadIdx.x; asm volatile("" : "+v"(tid)); const int lane = tid & 63, wid = __builtin_amdgcn_readfirstlane(tid >> 6); (void)lane; (void)wid;
;     const int bh = s >> 3, part = s & 7, h = bh % 6; const float G = exp2f(ret_log2gamma(h) * 128.f);
;     const size_t e = (size_t)bh * 64 * 16384 + part * 2048 + tid * 4; f32x4 st = (f32x4){0.f, 0.f, 0.f, 0.f};
; #pragma unroll 8
;     for (int i = 0; i < 64; ++i) { const f32x4 cur = *(const f32x4*)(KVT + e + (size_t)i * 16384); st_sc1_u2(RT + e + (size_t)i * 16384, pk2(st[0], st[1]), pk2(st[2], st[3])); st = cur + st * G; }
; }
.LBB0_268:
	v_mov_b32_e32 v3, v2
	s_mov_b32 s20, 0xfff90000
	v_add_co_u32_e32 v24, vcc, s20, v8
	s_nop 1
	v_addc_co_u32_e32 v25, vcc, -1, v9, vcc
	s_mov_b32 s20, 0x33600000
	v_add_co_u32_e32 v26, vcc, s20, v6
	s_nop 1
	v_addc_co_u32_e32 v27, vcc, 0, v7, vcc
	s_mov_b64 s[42:43], 0x10000
	s_mov_b64 s[46:47], 0x8000
	global_load_dwordx4 v[64:67], v[24:25], off
	v_lshl_add_u64 v[24:25], v[24:25], 0, s[42:43]
	global_load_dwordx4 v[68:71], v[24:25], off
	v_lshl_add_u64 v[24:25], v[24:25], 0, s[42:43]
	global_load_dwordx4 v[72:75], v[24:25], off
	v_lshl_add_u64 v[24:25], v[24:25], 0, s[42:43]
	global_load_dwordx4 v[76:79], v[24:25], off
	v_lshl_add_u64 v[24:25], v[24:25], 0, s[42:43]
	global_load_dwordx4 v[80:83], v[24:25], off
	v_lshl_add_u64 v[24:25], v[24:25], 0, s[42:43]
	global_load_dwordx4 v[84:87], v[24:25], off
	v_lshl_add_u64 v[24:25], v[24:25], 0, s[42:43]
	global_load_dwordx4 v[88:91], v[24:25], off
	v_lshl_add_u64 v[24:25], v[24:25], 0, s[42:43]
	global_load_dwordx4 v[92:95], v[24:25], off
	v_lshl_add_u64 v[24:25], v[24:25], 0, s[42:43]
	global_load_dwordx4 v[96:99], v[24:25], off
	v_lshl_add_u64 v[24:25], v[24:25], 0, s[42:43]
	global_load_dwordx4 v[100:103], v[24:25], off
	v_lshl_add_u64 v[24:25], v[24:25], 0, s[42:43]
	global_load_dwordx4 v[104:107], v[24:25], off
	v_lshl_add_u64 v[24:25], v[24:25], 0, s[42:43]
	global_load_dwordx4 v[108:111], v[24:25], off
	v_lshl_add_u64 v[24:25], v[24:25], 0, s[42:43]
	global_load_dwordx4 v[112:115], v[24:25], off
	v_lshl_add_u64 v[24:25], v[24:25], 0, s[42:43]
	global_load_dwordx4 v[116:119], v[24:25], off
	v_lshl_add_u64 v[24:25], v[24:25], 0, s[42:43]
	global_load_dwordx4 v[120:123], v[24:25], off
	v_lshl_add_u64 v[24:25], v[24:25], 0, s[42:43]
	global_load_dwordx4 v[124:127], v[24:25], off
	v_lshl_add_u64 v[24:25], v[24:25], 0, s[42:43]
	global_load_dwordx4 v[128:131], v[24:25], off
	v_lshl_add_u64 v[24:25], v[24:25], 0, s[42:43]
	global_load_dwordx4 v[132:135], v[24:25], off
	v_lshl_add_u64 v[24:25], v[24:25], 0, s[42:43]
	global_load_dwordx4 v[136:139], v[24:25], off
	v_lshl_add_u64 v[24:25], v[24:25], 0, s[42:43]
	global_load_dwordx4 v[140:143], v[24:25], off
	v_lshl_add_u64 v[24:25], v[24:25], 0, s[42:43]
	global_load_dwordx4 v[144:147], v[24:25], off
	v_lshl_add_u64 v[24:25], v[24:25], 0, s[42:43]
	global_load_dwordx4 v[148:151], v[24:25], off
	v_lshl_add_u64 v[24:25], v[24:25], 0, s[42:43]
	global_load_dwordx4 v[152:155], v[24:25], off
	v_lshl_add_u64 v[24:25], v[24:25], 0, s[42:43]
	global_load_dwordx4 v[156:159], v[24:25], off
	v_lshl_add_u64 v[24:25], v[24:25], 0, s[42:43]
	global_load_dwordx4 v[160:163], v[24:25], off
	v_lshl_add_u64 v[24:25], v[24:25], 0, s[42:43]
	global_load_dwordx4 v[164:167], v[24:25], off
	v_lshl_add_u64 v[24:25], v[24:25], 0, s[42:43]
	global_load_dwordx4 v[168:171], v[24:25], off
	v_lshl_add_u64 v[24:25], v[24:25], 0, s[42:43]
	global_load_dwordx4 v[172:175], v[24:25], off
	v_lshl_add_u64 v[24:25], v[24:25], 0, s[42:43]
	global_load_dwordx4 v[176:179], v[24:25], off
	v_lshl_add_u64 v[24:25], v[24:25], 0, s[42:43]
	global_load_dwordx4 v[180:183], v[24:25], off
	v_lshl_add_u64 v[24:25], v[24:25], 0, s[42:43]
	global_load_dwordx4 v[184:187], v[24:25], off
	v_lshl_add_u64 v[24:25], v[24:25], 0, s[42:43]
	global_load_dwordx4 v[188:191], v[24:25], off
	v_lshl_add_u64 v[24:25], v[24:25], 0, s[42:43]
	v_cvt_pk_bf16_f32 v22, v12, v13
	v_cvt_pk_bf16_f32 v23, v14, v15
	global_store_dwordx2 v[26:27], v[22:23], off sc1
	v_lshl_add_u64 v[26:27], v[26:27], 0, s[46:47]
	s_waitcnt vmcnt(31)
	v_pk_fma_f32 v[12:13], v[4:5], v[12:13], v[64:65]
	v_pk_fma_f32 v[14:15], v[2:3], v[14:15], v[66:67]
	global_load_dwordx4 v[64:67], v[24:25], off
	v_lshl_add_u64 v[24:25], v[24:25], 0, s[42:43]
	v_cvt_pk_bf16_f32 v28, v12, v13
	v_cvt_pk_bf16_f32 v29, v14, v15
	global_store_dwordx2 v[26:27], v[28:29], off sc1
	v_lshl_add_u64 v[26:27], v[26:27], 0, s[46:47]
	s_waitcnt vmcnt(31)
	v_pk_fma_f32 v[12:13], v[4:5], v[12:13], v[68:69]
	v_pk_fma_f32 v[14:15], v[2:3], v[14:15], v[70:71]
	global_load_dwordx4 v[68:71], v[24:25], off
	v_lshl_add_u64 v[24:25], v[24:25], 0, s[42:43]
	v_cvt_pk_bf16_f32 v22, v12, v13
	v_cvt_pk_bf16_f32 v23, v14, v15
	global_store_dwordx2 v[26:27], v[22:23], off sc1
	v_lshl_add_u64 v[26:27], v[26:27], 0, s[46:47]
	s_waitcnt vmcnt(31)
	v_pk_fma_f32 v[12:13], v[4:5], v[12:13], v[72:73]
	v_pk_fma_f32 v[14:15], v[2:3], v[14:15], v[74:75]
	global_load_dwordx4 v[72:75], v[24:25], off
	v_lshl_add_u64 v[24:25], v[24:25], 0, s[42:43]
	v_cvt_pk_bf16_f32 v28, v12, v13
	v_cvt_pk_bf16_f32 v29, v14, v15
	global_store_dwordx2 v[26:27], v[28:29], off sc1
	v_lshl_add_u64 v[26:27], v[26:27], 0, s[46:47]
	s_waitcnt vmcnt(31)
	v_pk_fma_f32 v[12:13], v[4:5], v[12:13], v[76:77]
	v_pk_fma_f32 v[14:15], v[2:3], v[14:15], v[78:79]
	global_load_dwordx4 v[76:79], v[24:25], off
	v_lshl_add_u64 v[24:25], v[24:25], 0, s[42:43]
	v_cvt_pk_bf16_f32 v22, v12, v13
	v_cvt_pk_bf16_f32 v23, v14, v15
	global_store_dwordx2 v[26:27], v[22:23], off sc1
	v_lshl_add_u64 v[26:27], v[26:27], 0, s[46:47]
	s_waitcnt vmcnt(31)
	v_pk_fma_f32 v[12:13], v[4:5], v[12:13], v[80:81]
	v_pk_fma_f32 v[14:15], v[2:3], v[14:15], v[82:83]
	global_load_dwordx4 v[80:83], v[24:25], off
	v_lshl_add_u64 v[24:25], v[24:25], 0, s[42:43]
	v_cvt_pk_bf16_f32 v28, v12, v13
	v_cvt_pk_bf16_f32 v29, v14, v15
	global_store_dwordx2 v[26:27], v[28:29], off sc1
	v_lshl_add_u64 v[26:27], v[26:27], 0, s[46:47]
	s_waitcnt vmcnt(31)
	v_pk_fma_f32 v[12:13], v[4:5], v[12:13], v[84:85]
	v_pk_fma_f32 v[14:15], v[2:3], v[14:15], v[86:87]
	global_load_dwordx4 v[84:87], v[24:25], off
	v_lshl_add_u64 v[24:25], v[24:25], 0, s[42:43]
	v_cvt_pk_bf16_f32 v22, v12, v13
	v_cvt_pk_bf16_f32 v23, v14, v15
	global_store_dwordx2 v[26:27], v[22:23], off sc1
	v_lshl_add_u64 v[26:27], v[26:27], 0, s[46:47]
	s_waitcnt vmcnt(31)
; __device__ __forceinline__ unsigned pk2(float lo, float hi) { return pg8::cvt_pk_bf16(lo, hi); }
; __device__ __forceinline__ void st_sc1_u2(void* p, unsigned lo, unsigned hi) { __hip_atomic_store((GAS unsigned long long*)p, ((unsigned long long)hi << 32) | (unsigned long long)lo, __ATOMIC_RELAXED, __HIP_MEMORY_SCOPE_AGENT); }
; __device__ __forceinline__ void scan_unit(const float* KVT, bfu* RT, int s) {
;     ...
; #pragma unroll 8
;     for (int i = 0; i < 64; ++i) { const f32x4 cur = *(const f32x4*)(KVT + e + (size_t)i * 16384); st_sc1_u2(RT + e + (size_t)i * 16384, pk2(st[0], st[1]), pk2(st[2], st[3])); st = cur + st * G; }
	v_pk_fma_f32 v[12:13], v[4:5], v[12:13], v[88:89]
	v_pk_fma_f32 v[14:15], v[2:3], v[14:15], v[90:91]
	global_load_dwordx4 v[88:91], v[24:25], off
	v_lshl_add_u64 v[24:25], v[24:25], 0, s[42:43]
	v_cvt_pk_bf16_f32 v28, v12, v13
	v_cvt_pk_bf16_f32 v29, v14, v15
	global_store_dwordx2 v[26:27], v[28:29], off sc1
	v_lshl_add_u64 v[26:27], v[26:27], 0, s[46:47]
	s_waitcnt vmcnt(31)
	v_pk_fma_f32 v[12:13], v[4:5], v[12:13], v[92:93]
	v_pk_fma_f32 v[14:15], v[2:3], v[14:15], v[94:95]
	global_load_dwordx4 v[92:95], v[24:25], off
	v_lshl_add_u64 v[24:25], v[24:25], 0, s[42:43]
	v_cvt_pk_bf16_f32 v22, v12, v13
	v_cvt_pk_bf16_f32 v23, v14, v15
	global_store_dwordx2 v[26:27], v[22:23], off sc1
	v_lshl_add_u64 v[26:27], v[26:27], 0, s[46:47]
	s_waitcnt vmcnt(31)
	v_pk_fma_f32 v[12:13], v[4:5], v[12:13], v[96:97]
	v_pk_fma_f32 v[14:15], v[2:3], v[14:15], v[98:99]
	global_load_dwordx4 v[96:99], v[24:25], off
	v_lshl_add_u64 v[24:25], v[24:25], 0, s[42:43]
	v_cvt_pk_bf16_f32 v28, v12, v13
	v_cvt_pk_bf16_f32 v29, v14, v15
	global_store_dwordx2 v[26:27], v[28:29], off sc1
	v_lshl_add_u64 v[26:27], v[26:27], 0, s[46:47]
	s_waitcnt vmcnt(31)
	v_pk_fma_f32 v[12:13], v[4:5], v[12:13], v[100:101]
	v_pk_fma_f32 v[14:15], v[2:3], v[14:15], v[102:103]
	global_load_dwordx4 v[100:103], v[24:25], off
	v_lshl_add_u64 v[24:25], v[24:25], 0, s[42:43]
	v_cvt_pk_bf16_f32 v22, v12, v13
	v_cvt_pk_bf16_f32 v23, v14, v15
	global_store_dwordx2 v[26:27], v[22:23], off sc1
	v_lshl_add_u64 v[26:27], v[26:27], 0, s[46:47]
	s_waitcnt vmcnt(31)
	v_pk_fma_f32 v[12:13], v[4:5], v[12:13], v[104:105]
	v_pk_fma_f32 v[14:15], v[2:3], v[14:15], v[106:107]
	global_load_dwordx4 v[104:107], v[24:25], off
	v_lshl_add_u64 v[24:25], v[24:25], 0, s[42:43]
	v_cvt_pk_bf16_f32 v28, v12, v13
	v_cvt_pk_bf16_f32 v29, v14, v15
	global_store_dwordx2 v[26:27], v[28:29], off sc1
	v_lshl_add_u64 v[26:27], v[26:27], 0, s[46:47]
	s_waitcnt vmcnt(31)
	v_pk_fma_f32 v[12:13], v[4:5], v[12:13], v[108:109]
	v_pk_fma_f32 v[14:15], v[2:3], v[14:15], v[110:111]
	global_load_dwordx4 v[108:111], v[24:25], off
	v_lshl_add_u64 v[24:25], v[24:25], 0, s[42:43]
	v_cvt_pk_bf16_f32 v22, v12, v13
	v_cvt_pk_bf16_f32 v23, v14, v15
	global_store_dwordx2 v[26:27], v[22:23], off sc1
	v_lshl_add_u64 v[26:27], v[26:27], 0, s[46:47]
	s_waitcnt vmcnt(31)
	v_pk_fma_f32 v[12:13], v[4:5], v[12:13], v[112:113]
	v_pk_fma_f32 v[14:15], v[2:3], v[14:15], v[114:115]
	global_load_dwordx4 v[112:115], v[24:25], off
	v_lshl_add_u64 v[24:25], v[24:25], 0, s[42:43]
	v_cvt_pk_bf16_f32 v28, v12, v13
	v_cvt_pk_bf16_f32 v29, v14, v15
	global_store_dwordx2 v[26:27], v[28:29], off sc1
	v_lshl_add_u64 v[26:27], v[26:27], 0, s[46:47]
	s_waitcnt vmcnt(31)
	v_pk_fma_f32 v[12:13], v[4:5], v[12:13], v[116:117]
	v_pk_fma_f32 v[14:15], v[2:3], v[14:15], v[118:119]
	global_load_dwordx4 v[116:119], v[24:25], off
	v_lshl_add_u64 v[24:25], v[24:25], 0, s[42:43]
	v_cvt_pk_bf16_f32 v22, v12, v13
	v_cvt_pk_bf16_f32 v23, v14, v15
	global_store_dwordx2 v[26:27], v[22:23], off sc1
	v_lshl_add_u64 v[26:27], v[26:27], 0, s[46:47]
	s_waitcnt vmcnt(31)
	v_pk_fma_f32 v[12:13], v[4:5], v[12:13], v[120:121]
	v_pk_fma_f32 v[14:15], v[2:3], v[14:15], v[122:123]
	global_load_dwordx4 v[120:123], v[24:25], off
	v_lshl_add_u64 v[24:25], v[24:25], 0, s[42:43]
	v_cvt_pk_bf16_f32 v28, v12, v13
	v_cvt_pk_bf16_f32 v29, v14, v15
	global_store_dwordx2 v[26:27], v[28:29], off sc1
	v_lshl_add_u64 v[26:27], v[26:27], 0, s[46:47]
	s_waitcnt vmcnt(31)
	v_pk_fma_f32 v[12:13], v[4:5], v[12:13], v[124:125]
	v_pk_fma_f32 v[14:15], v[2:3], v[14:15], v[126:127]
	global_load_dwordx4 v[124:127], v[24:25], off
	v_lshl_add_u64 v[24:25], v[24:25], 0, s[42:43]
	v_cvt_pk_bf16_f32 v22, v12, v13
	v_cvt_pk_bf16_f32 v23, v14, v15
	global_store_dwordx2 v[26:27], v[22:23], off sc1
	v_lshl_add_u64 v[26:27], v[26:27], 0, s[46:47]
	s_waitcnt vmcnt(31)
	v_pk_fma_f32 v[12:13], v[4:5], v[12:13], v[128:129]
	v_pk_fma_f32 v[14:15], v[2:3], v[14:15], v[130:131]
	global_load_dwordx4 v[128:131], v[24:25], off
	v_lshl_add_u64 v[24:25], v[24:25], 0, s[42:43]
	v_cvt_pk_bf16_f32 v28, v12, v13
	v_cvt_pk_bf16_f32 v29, v14, v15
	global_store_dwordx2 v[26:27], v[28:29], off sc1
	v_lshl_add_u64 v[26:27], v[26:27], 0, s[46:47]
	s_waitcnt vmcnt(31)
	v_pk_fma_f32 v[12:13], v[4:5], v[12:13], v[132:133]
	v_pk_fma_f32 v[14:15], v[2:3], v[14:15], v[134:135]
	global_load_dwordx4 v[132:135], v[24:25], off
	v_lshl_add_u64 v[24:25], v[24:25], 0, s[42:43]
	v_cvt_pk_bf16_f32 v22, v12, v13
	v_cvt_pk_bf16_f32 v23, v14, v15
	global_store_dwordx2 v[26:27], v[22:23], off sc1
	v_lshl_add_u64 v[26:27], v[26:27], 0, s[46:47]
	s_waitcnt vmcnt(31)
	v_pk_fma_f32 v[12:13], v[4:5], v[12:13], v[136:137]
	v_pk_fma_f32 v[14:15], v[2:3], v[14:15], v[138:139]
	global_load_dwordx4 v[136:139], v[24:25], off
	v_lshl_add_u64 v[24:25], v[24:25], 0, s[42:43]
	v_cvt_pk_bf16_f32 v28, v12, v13
	v_cvt_pk_bf16_f32 v29, v14, v15
	global_store_dwordx2 v[26:27], v[28:29], off sc1
	v_lshl_add_u64 v[26:27], v[26:27], 0, s[46:47]
	s_waitcnt vmcnt(31)
	v_pk_fma_f32 v[12:13], v[4:5], v[12:13], v[140:141]
	v_pk_fma_f32 v[14:15], v[2:3], v[14:15], v[142:143]
	global_load_dwordx4 v[140:143], v[24:25], off
	v_lshl_add_u64 v[24:25], v[24:25], 0, s[42:43]
	v_cvt_pk_bf16_f32 v22, v12, v13
	v_cvt_pk_bf16_f32 v23, v14, v15
	global_store_dwordx2 v[26:27], v[22:23], off sc1
	v_lshl_add_u64 v[26:27], v[26:27], 0, s[46:47]
	s_waitcnt vmcnt(31)
	v_pk_fma_f32 v[12:13], v[4:5], v[12:13], v[144:145]
	v_pk_fma_f32 v[14:15], v[2:3], v[14:15], v[146:147]
	global_load_dwordx4 v[144:147], v[24:25], off
	v_lshl_add_u64 v[24:25], v[24:25], 0, s[42:43]
	v_cvt_pk_bf16_f32 v28, v12, v13
	v_cvt_pk_bf16_f32 v29, v14, v15
	global_store_dwordx2 v[26:27], v[28:29], off sc1
	v_lshl_add_u64 v[26:27], v[26:27], 0, s[46:47]
	s_waitcnt vmcnt(31)
; __device__ __forceinline__ unsigned pk2(float lo, float hi) { return pg8::cvt_pk_bf16(lo, hi); }
; __device__ __forceinline__ void st_sc1_u2(void* p, unsigned lo, unsigned hi) { __hip_atomic_store((GAS unsigned long long*)p, ((unsigned long long)hi << 32) | (unsigned long long)lo, __ATOMIC_RELAXED, __HIP_MEMORY_SCOPE_AGENT); }
; __device__ __forceinline__ void scan_unit(const float* KVT, bfu* RT, int s) {
;     ...
; #pragma unroll 8
;     for (int i = 0; i < 64; ++i) { const f32x4 cur = *(const f32x4*)(KVT + e + (size_t)i * 16384); st_sc1_u2(RT + e + (size_t)i * 16384, pk2(st[0], st[1]), pk2(st[2], st[3])); st = cur + st * G; }
	v_pk_fma_f32 v[12:13], v[4:5], v[12:13], v[148:149]
	v_pk_fma_f32 v[14:15], v[2:3], v[14:15], v[150:151]
	global_load_dwordx4 v[148:151], v[24:25], off
	v_lshl_add_u64 v[24:25], v[24:25], 0, s[42:43]
	v_cvt_pk_bf16_f32 v22, v12, v13
	v_cvt_pk_bf16_f32 v23, v14, v15
	global_store_dwordx2 v[26:27], v[22:23], off sc1
	v_lshl_add_u64 v[26:27], v[26:27], 0, s[46:47]
	s_waitcnt vmcnt(31)
	v_pk_fma_f32 v[12:13], v[4:5], v[12:13], v[152:153]
	v_pk_fma_f32 v[14:15], v[2:3], v[14:15], v[154:155]
	global_load_dwordx4 v[152:155], v[24:25], off
	v_lshl_add_u64 v[24:25], v[24:25], 0, s[42:43]
	v_cvt_pk_bf16_f32 v28, v12, v13
	v_cvt_pk_bf16_f32 v29, v14, v15
	global_store_dwordx2 v[26:27], v[28:29], off sc1
	v_lshl_add_u64 v[26:27], v[26:27], 0, s[46:47]
	s_waitcnt vmcnt(31)
	v_pk_fma_f32 v[12:13], v[4:5], v[12:13], v[156:157]
	v_pk_fma_f32 v[14:15], v[2:3], v[14:15], v[158:159]
	global_load_dwordx4 v[156:159], v[24:25], off
	v_lshl_add_u64 v[24:25], v[24:25], 0, s[42:43]
	v_cvt_pk_bf16_f32 v22, v12, v13
	v_cvt_pk_bf16_f32 v23, v14, v15
	global_store_dwordx2 v[26:27], v[22:23], off sc1
	v_lshl_add_u64 v[26:27], v[26:27], 0, s[46:47]
	s_waitcnt vmcnt(31)
	v_pk_fma_f32 v[12:13], v[4:5], v[12:13], v[160:161]
	v_pk_fma_f32 v[14:15], v[2:3], v[14:15], v[162:163]
	global_load_dwordx4 v[160:163], v[24:25], off
	v_lshl_add_u64 v[24:25], v[24:25], 0, s[42:43]
	v_cvt_pk_bf16_f32 v28, v12, v13
	v_cvt_pk_bf16_f32 v29, v14, v15
	global_store_dwordx2 v[26:27], v[28:29], off sc1
	v_lshl_add_u64 v[26:27], v[26:27], 0, s[46:47]
	s_waitcnt vmcnt(31)
	v_pk_fma_f32 v[12:13], v[4:5], v[12:13], v[164:165]
	v_pk_fma_f32 v[14:15], v[2:3], v[14:15], v[166:167]
	global_load_dwordx4 v[164:167], v[24:25], off
	v_lshl_add_u64 v[24:25], v[24:25], 0, s[42:43]
	v_cvt_pk_bf16_f32 v22, v12, v13
	v_cvt_pk_bf16_f32 v23, v14, v15
	global_store_dwordx2 v[26:27], v[22:23], off sc1
	v_lshl_add_u64 v[26:27], v[26:27], 0, s[46:47]
	s_waitcnt vmcnt(31)
	v_pk_fma_f32 v[12:13], v[4:5], v[12:13], v[168:169]
	v_pk_fma_f32 v[14:15], v[2:3], v[14:15], v[170:171]
	global_load_dwordx4 v[168:171], v[24:25], off
	v_lshl_add_u64 v[24:25], v[24:25], 0, s[42:43]
	v_cvt_pk_bf16_f32 v28, v12, v13
	v_cvt_pk_bf16_f32 v29, v14, v15
	global_store_dwordx2 v[26:27], v[28:29], off sc1
	v_lshl_add_u64 v[26:27], v[26:27], 0, s[46:47]
	s_waitcnt vmcnt(31)
	v_pk_fma_f32 v[12:13], v[4:5], v[12:13], v[172:173]
	v_pk_fma_f32 v[14:15], v[2:3], v[14:15], v[174:175]
	global_load_dwordx4 v[172:175], v[24:25], off
	v_lshl_add_u64 v[24:25], v[24:25], 0, s[42:43]
	v_cvt_pk_bf16_f32 v22, v12, v13
	v_cvt_pk_bf16_f32 v23, v14, v15
	global_store_dwordx2 v[26:27], v[22:23], off sc1
	v_lshl_add_u64 v[26:27], v[26:27], 0, s[46:47]
	s_waitcnt vmcnt(31)
	v_pk_fma_f32 v[12:13], v[4:5], v[12:13], v[176:177]
	v_pk_fma_f32 v[14:15], v[2:3], v[14:15], v[178:179]
	global_load_dwordx4 v[176:179], v[24:25], off
	v_lshl_add_u64 v[24:25], v[24:25], 0, s[42:43]
	v_cvt_pk_bf16_f32 v28, v12, v13
	v_cvt_pk_bf16_f32 v29, v14, v15
	global_store_dwordx2 v[26:27], v[28:29], off sc1
	v_lshl_add_u64 v[26:27], v[26:27], 0, s[46:47]
	s_waitcnt vmcnt(31)
	v_pk_fma_f32 v[12:13], v[4:5], v[12:13], v[180:181]
	v_pk_fma_f32 v[14:15], v[2:3], v[14:15], v[182:183]
	global_load_dwordx4 v[180:183], v[24:25], off
	v_lshl_add_u64 v[24:25], v[24:25], 0, s[42:43]
	v_cvt_pk_bf16_f32 v22, v12, v13
	v_cvt_pk_bf16_f32 v23, v14, v15
	global_store_dwordx2 v[26:27], v[22:23], off sc1
	v_lshl_add_u64 v[26:27], v[26:27], 0, s[46:47]
	s_waitcnt vmcnt(31)
	v_pk_fma_f32 v[12:13], v[4:5], v[12:13], v[184:185]
	v_pk_fma_f32 v[14:15], v[2:3], v[14:15], v[186:187]
	global_load_dwordx4 v[184:187], v[24:25], off
	v_lshl_add_u64 v[24:25], v[24:25], 0, s[42:43]
	v_cvt_pk_bf16_f32 v28, v12, v13
	v_cvt_pk_bf16_f32 v29, v14, v15
	global_store_dwordx2 v[26:27], v[28:29], off sc1
	v_lshl_add_u64 v[26:27], v[26:27], 0, s[46:47]
	s_waitcnt vmcnt(31)
	v_pk_fma_f32 v[12:13], v[4:5], v[12:13], v[188:189]
	v_pk_fma_f32 v[14:15], v[2:3], v[14:15], v[190:191]
	global_load_dwordx4 v[188:191], v[24:25], off
	v_lshl_add_u64 v[24:25], v[24:25], 0, s[42:43]
	v_cvt_pk_bf16_f32 v22, v12, v13
	v_cvt_pk_bf16_f32 v23, v14, v15
	global_store_dwordx2 v[26:27], v[22:23], off sc1
	v_lshl_add_u64 v[26:27], v[26:27], 0, s[46:47]
	s_waitcnt vmcnt(31)
	v_pk_fma_f32 v[12:13], v[4:5], v[12:13], v[64:65]
	v_pk_fma_f32 v[14:15], v[2:3], v[14:15], v[66:67]
	v_cvt_pk_bf16_f32 v28, v12, v13
	v_cvt_pk_bf16_f32 v29, v14, v15
	global_store_dwordx2 v[26:27], v[28:29], off sc1
	v_lshl_add_u64 v[26:27], v[26:27], 0, s[46:47]
	s_waitcnt vmcnt(30)
	v_pk_fma_f32 v[12:13], v[4:5], v[12:13], v[68:69]
	v_pk_fma_f32 v[14:15], v[2:3], v[14:15], v[70:71]
	v_cvt_pk_bf16_f32 v22, v12, v13
	v_cvt_pk_bf16_f32 v23, v14, v15
	global_store_dwordx2 v[26:27], v[22:23], off sc1
	v_lshl_add_u64 v[26:27], v[26:27], 0, s[46:47]
	s_waitcnt vmcnt(29)
	v_pk_fma_f32 v[12:13], v[4:5], v[12:13], v[72:73]
	v_pk_fma_f32 v[14:15], v[2:3], v[14:15], v[74:75]
	v_cvt_pk_bf16_f32 v28, v12, v13
	v_cvt_pk_bf16_f32 v29, v14, v15
	global_store_dwordx2 v[26:27], v[28:29], off sc1
	v_lshl_add_u64 v[26:27], v[26:27], 0, s[46:47]
	s_waitcnt vmcnt(28)
	v_pk_fma_f32 v[12:13], v[4:5], v[12:13], v[76:77]
	v_pk_fma_f32 v[14:15], v[2:3], v[14:15], v[78:79]
	v_cvt_pk_bf16_f32 v22, v12, v13
	v_cvt_pk_bf16_f32 v23, v14, v15
	global_store_dwordx2 v[26:27], v[22:23], off sc1
	v_lshl_add_u64 v[26:27], v[26:27], 0, s[46:47]
	s_waitcnt vmcnt(27)
	v_pk_fma_f32 v[12:13], v[4:5], v[12:13], v[80:81]
	v_pk_fma_f32 v[14:15], v[2:3], v[14:15], v[82:83]
	v_cvt_pk_bf16_f32 v28, v12, v13
	v_cvt_pk_bf16_f32 v29, v14, v15
	global_store_dwordx2 v[26:27], v[28:29], off sc1
	v_lshl_add_u64 v[26:27], v[26:27], 0, s[46:47]
	s_waitcnt vmcnt(26)
; __device__ __forceinline__ unsigned pk2(float lo, float hi) { return pg8::cvt_pk_bf16(lo, hi); }
; __device__ __forceinline__ void st_sc1_u2(void* p, unsigned lo, unsigned hi) { __hip_atomic_store((GAS unsigned long long*)p, ((unsigned long long)hi << 32) | (unsigned long long)lo, __ATOMIC_RELAXED, __HIP_MEMORY_SCOPE_AGENT); }
; __device__ __forceinline__ void scan_unit(const float* KVT, bfu* RT, int s) {
;     ...
; #pragma unroll 8
;     for (int i = 0; i < 64; ++i) { const f32x4 cur = *(const f32x4*)(KVT + e + (size_t)i * 16384); st_sc1_u2(RT + e + (size_t)i * 16384, pk2(st[0], st[1]), pk2(st[2], st[3])); st = cur + st * G; }
	v_pk_fma_f32 v[12:13], v[4:5], v[12:13], v[84:85]
	v_pk_fma_f32 v[14:15], v[2:3], v[14:15], v[86:87]
	v_cvt_pk_bf16_f32 v22, v12, v13
	v_cvt_pk_bf16_f32 v23, v14, v15
	global_store_dwordx2 v[26:27], v[22:23], off sc1
	v_lshl_add_u64 v[26:27], v[26:27], 0, s[46:47]
	s_waitcnt vmcnt(25)
	v_pk_fma_f32 v[12:13], v[4:5], v[12:13], v[88:89]
	v_pk_fma_f32 v[14:15], v[2:3], v[14:15], v[90:91]
	v_cvt_pk_bf16_f32 v28, v12, v13
	v_cvt_pk_bf16_f32 v29, v14, v15
	global_store_dwordx2 v[26:27], v[28:29], off sc1
	v_lshl_add_u64 v[26:27], v[26:27], 0, s[46:47]
	s_waitcnt vmcnt(24)
	v_pk_fma_f32 v[12:13], v[4:5], v[12:13], v[92:93]
	v_pk_fma_f32 v[14:15], v[2:3], v[14:15], v[94:95]
	v_cvt_pk_bf16_f32 v22, v12, v13
	v_cvt_pk_bf16_f32 v23, v14, v15
	global_store_dwordx2 v[26:27], v[22:23], off sc1
	v_lshl_add_u64 v[26:27], v[26:27], 0, s[46:47]
	s_waitcnt vmcnt(23)
	v_pk_fma_f32 v[12:13], v[4:5], v[12:13], v[96:97]
	v_pk_fma_f32 v[14:15], v[2:3], v[14:15], v[98:99]
	v_cvt_pk_bf16_f32 v28, v12, v13
	v_cvt_pk_bf16_f32 v29, v14, v15
	global_store_dwordx2 v[26:27], v[28:29], off sc1
	v_lshl_add_u64 v[26:27], v[26:27], 0, s[46:47]
	s_waitcnt vmcnt(22)
	v_pk_fma_f32 v[12:13], v[4:5], v[12:13], v[100:101]
	v_pk_fma_f32 v[14:15], v[2:3], v[14:15], v[102:103]
	v_cvt_pk_bf16_f32 v22, v12, v13
	v_cvt_pk_bf16_f32 v23, v14, v15
	global_store_dwordx2 v[26:27], v[22:23], off sc1
	v_lshl_add_u64 v[26:27], v[26:27], 0, s[46:47]
	s_waitcnt vmcnt(21)
	v_pk_fma_f32 v[12:13], v[4:5], v[12:13], v[104:105]
	v_pk_fma_f32 v[14:15], v[2:3], v[14:15], v[106:107]
	v_cvt_pk_bf16_f32 v28, v12, v13
	v_cvt_pk_bf16_f32 v29, v14, v15
	global_store_dwordx2 v[26:27], v[28:29], off sc1
	v_lshl_add_u64 v[26:27], v[26:27], 0, s[46:47]
	s_waitcnt vmcnt(20)
	v_pk_fma_f32 v[12:13], v[4:5], v[12:13], v[108:109]
	v_pk_fma_f32 v[14:15], v[2:3], v[14:15], v[110:111]
	v_cvt_pk_bf16_f32 v22, v12, v13
	v_cvt_pk_bf16_f32 v23, v14, v15
	global_store_dwordx2 v[26:27], v[22:23], off sc1
	v_lshl_add_u64 v[26:27], v[26:27], 0, s[46:47]
	s_waitcnt vmcnt(19)
	v_pk_fma_f32 v[12:13], v[4:5], v[12:13], v[112:113]
	v_pk_fma_f32 v[14:15], v[2:3], v[14:15], v[114:115]
	v_cvt_pk_bf16_f32 v28, v12, v13
	v_cvt_pk_bf16_f32 v29, v14, v15
	global_store_dwordx2 v[26:27], v[28:29], off sc1
	v_lshl_add_u64 v[26:27], v[26:27], 0, s[46:47]
	s_waitcnt vmcnt(18)
	v_pk_fma_f32 v[12:13], v[4:5], v[12:13], v[116:117]
	v_pk_fma_f32 v[14:15], v[2:3], v[14:15], v[118:119]
	v_cvt_pk_bf16_f32 v22, v12, v13
	v_cvt_pk_bf16_f32 v23, v14, v15
	global_store_dwordx2 v[26:27], v[22:23], off sc1
	v_lshl_add_u64 v[26:27], v[26:27], 0, s[46:47]
	s_waitcnt vmcnt(17)
	v_pk_fma_f32 v[12:13], v[4:5], v[12:13], v[120:121]
	v_pk_fma_f32 v[14:15], v[2:3], v[14:15], v[122:123]
	v_cvt_pk_bf16_f32 v28, v12, v13
	v_cvt_pk_bf16_f32 v29, v14, v15
	global_store_dwordx2 v[26:27], v[28:29], off sc1
	v_lshl_add_u64 v[26:27], v[26:27], 0, s[46:47]
	s_waitcnt vmcnt(16)
	v_pk_fma_f32 v[12:13], v[4:5], v[12:13], v[124:125]
	v_pk_fma_f32 v[14:15], v[2:3], v[14:15], v[126:127]
	v_cvt_pk_bf16_f32 v22, v12, v13
	v_cvt_pk_bf16_f32 v23, v14, v15
	global_store_dwordx2 v[26:27], v[22:23], off sc1
	v_lshl_add_u64 v[26:27], v[26:27], 0, s[46:47]
	s_waitcnt vmcnt(15)
	v_pk_fma_f32 v[12:13], v[4:5], v[12:13], v[128:129]
	v_pk_fma_f32 v[14:15], v[2:3], v[14:15], v[130:131]
	v_cvt_pk_bf16_f32 v28, v12, v13
	v_cvt_pk_bf16_f32 v29, v14, v15
	global_store_dwordx2 v[26:27], v[28:29], off sc1
	v_lshl_add_u64 v[26:27], v[26:27], 0, s[46:47]
	s_waitcnt vmcnt(14)
	v_pk_fma_f32 v[12:13], v[4:5], v[12:13], v[132:133]
	v_pk_fma_f32 v[14:15], v[2:3], v[14:15], v[134:135]
	v_cvt_pk_bf16_f32 v22, v12, v13
	v_cvt_pk_bf16_f32 v23, v14, v15
	global_store_dwordx2 v[26:27], v[22:23], off sc1
	v_lshl_add_u64 v[26:27], v[26:27], 0, s[46:47]
	s_waitcnt vmcnt(13)
	v_pk_fma_f32 v[12:13], v[4:5], v[12:13], v[136:137]
	v_pk_fma_f32 v[14:15], v[2:3], v[14:15], v[138:139]
	v_cvt_pk_bf16_f32 v28, v12, v13
	v_cvt_pk_bf16_f32 v29, v14, v15
	global_store_dwordx2 v[26:27], v[28:29], off sc1
	v_lshl_add_u64 v[26:27], v[26:27], 0, s[46:47]
	s_waitcnt vmcnt(12)
; __device__ __forceinline__ unsigned pk2(float lo, float hi) { return pg8::cvt_pk_bf16(lo, hi); }
; __device__ __forceinline__ void st_sc1_u2(void* p, unsigned lo, unsigned hi) { __hip_atomic_store((GAS unsigned long long*)p, ((unsigned long long)hi << 32) | (unsigned long long)lo, __ATOMIC_RELAXED, __HIP_MEMORY_SCOPE_AGENT); }
; __device__ __forceinline__ void scan_unit(const float* KVT, bfu* RT, int s) {
;     ...
; #pragma unroll 8
;     for (int i = 0; i < 64; ++i) { const f32x4 cur = *(const f32x4*)(KVT + e + (size_t)i * 16384); st_sc1_u2(RT + e + (size_t)i * 16384, pk2(st[0], st[1]), pk2(st[2], st[3])); st = cur + st * G; }
; }
; __global__ void __launch_bounds__(NTHR, 2) fwd(Args args) {
;     ...
;                 else { const int s_ = u - 768; wait_ge(cw + 64 + (s_ >> 3), 64u, cw + 192); scan_unit(KVT, RT, s_); publish(cw + 128 + (s_ >> 3)); }
	v_pk_fma_f32 v[12:13], v[4:5], v[12:13], v[140:141]
	v_pk_fma_f32 v[14:15], v[2:3], v[14:15], v[142:143]
	v_cvt_pk_bf16_f32 v22, v12, v13
	v_cvt_pk_bf16_f32 v23, v14, v15
	global_store_dwordx2 v[26:27], v[22:23], off sc1
	v_lshl_add_u64 v[26:27], v[26:27], 0, s[46:47]
	s_waitcnt vmcnt(11)
	v_pk_fma_f32 v[12:13], v[4:5], v[12:13], v[144:145]
	v_pk_fma_f32 v[14:15], v[2:3], v[14:15], v[146:147]
	v_cvt_pk_bf16_f32 v28, v12, v13
	v_cvt_pk_bf16_f32 v29, v14, v15
	global_store_dwordx2 v[26:27], v[28:29], off sc1
	v_lshl_add_u64 v[26:27], v[26:27], 0, s[46:47]
	s_waitcnt vmcnt(10)
	v_pk_fma_f32 v[12:13], v[4:5], v[12:13], v[148:149]
	v_pk_fma_f32 v[14:15], v[2:3], v[14:15], v[150:151]
	v_cvt_pk_bf16_f32 v22, v12, v13
	v_cvt_pk_bf16_f32 v23, v14, v15
	global_store_dwordx2 v[26:27], v[22:23], off sc1
	v_lshl_add_u64 v[26:27], v[26:27], 0, s[46:47]
	s_waitcnt vmcnt(9)
	v_pk_fma_f32 v[12:13], v[4:5], v[12:13], v[152:153]
	v_pk_fma_f32 v[14:15], v[2:3], v[14:15], v[154:155]
	v_cvt_pk_bf16_f32 v28, v12, v13
	v_cvt_pk_bf16_f32 v29, v14, v15
	global_store_dwordx2 v[26:27], v[28:29], off sc1
	v_lshl_add_u64 v[26:27], v[26:27], 0, s[46:47]
	s_waitcnt vmcnt(8)
	v_pk_fma_f32 v[12:13], v[4:5], v[12:13], v[156:157]
	v_pk_fma_f32 v[14:15], v[2:3], v[14:15], v[158:159]
	v_cvt_pk_bf16_f32 v22, v12, v13
	v_cvt_pk_bf16_f32 v23, v14, v15
	global_store_dwordx2 v[26:27], v[22:23], off sc1
	v_lshl_add_u64 v[26:27], v[26:27], 0, s[46:47]
	s_waitcnt vmcnt(7)
	v_pk_fma_f32 v[12:13], v[4:5], v[12:13], v[160:161]
	v_pk_fma_f32 v[14:15], v[2:3], v[14:15], v[162:163]
	v_cvt_pk_bf16_f32 v28, v12, v13
	v_cvt_pk_bf16_f32 v29, v14, v15
	global_store_dwordx2 v[26:27], v[28:29], off sc1
	v_lshl_add_u64 v[26:27], v[26:27], 0, s[46:47]
	s_waitcnt vmcnt(6)
	v_pk_fma_f32 v[12:13], v[4:5], v[12:13], v[164:165]
	v_pk_fma_f32 v[14:15], v[2:3], v[14:15], v[166:167]
	v_cvt_pk_bf16_f32 v22, v12, v13
	v_cvt_pk_bf16_f32 v23, v14, v15
	global_store_dwordx2 v[26:27], v[22:23], off sc1
	v_lshl_add_u64 v[26:27], v[26:27], 0, s[46:47]
	s_waitcnt vmcnt(5)
	v_pk_fma_f32 v[12:13], v[4:5], v[12:13], v[168:169]
	v_pk_fma_f32 v[14:15], v[2:3], v[14:15], v[170:171]
	v_cvt_pk_bf16_f32 v28, v12, v13
	v_cvt_pk_bf16_f32 v29, v14, v15
	global_store_dwordx2 v[26:27], v[28:29], off sc1
	v_lshl_add_u64 v[26:27], v[26:27], 0, s[46:47]
	s_waitcnt vmcnt(4)
	v_pk_fma_f32 v[12:13], v[4:5], v[12:13], v[172:173]
	v_pk_fma_f32 v[14:15], v[2:3], v[14:15], v[174:175]
	v_cvt_pk_bf16_f32 v22, v12, v13
	v_cvt_pk_bf16_f32 v23, v14, v15
	global_store_dwordx2 v[26:27], v[22:23], off sc1
	v_lshl_add_u64 v[26:27], v[26:27], 0, s[46:47]
	s_waitcnt vmcnt(3)
	v_pk_fma_f32 v[12:13], v[4:5], v[12:13], v[176:177]
	v_pk_fma_f32 v[14:15], v[2:3], v[14:15], v[178:179]
	v_cvt_pk_bf16_f32 v28, v12, v13
	v_cvt_pk_bf16_f32 v29, v14, v15
	global_store_dwordx2 v[26:27], v[28:29], off sc1
	v_lshl_add_u64 v[26:27], v[26:27], 0, s[46:47]
	s_waitcnt vmcnt(2)
	v_pk_fma_f32 v[12:13], v[4:5], v[12:13], v[180:181]
	v_pk_fma_f32 v[14:15], v[2:3], v[14:15], v[182:183]
	v_cvt_pk_bf16_f32 v22, v12, v13
	v_cvt_pk_bf16_f32 v23, v14, v15
	global_store_dwordx2 v[26:27], v[22:23], off sc1
	v_lshl_add_u64 v[26:27], v[26:27], 0, s[46:47]
	s_waitcnt vmcnt(1)
	v_pk_fma_f32 v[12:13], v[4:5], v[12:13], v[184:185]
	v_pk_fma_f32 v[14:15], v[2:3], v[14:15], v[186:187]
	v_cvt_pk_bf16_f32 v28, v12, v13
	v_cvt_pk_bf16_f32 v29, v14, v15
	global_store_dwordx2 v[26:27], v[28:29], off sc1
	v_lshl_add_u64 v[26:27], v[26:27], 0, s[46:47]
	s_waitcnt vmcnt(0)
	v_pk_fma_f32 v[12:13], v[4:5], v[12:13], v[188:189]
	v_pk_fma_f32 v[14:15], v[2:3], v[14:15], v[190:191]
	s_waitcnt vmcnt(0)
	s_mov_b64 s[46:47], 0
	s_mov_b64 s[42:43], 0
	s_barrier
	s_and_saveexec_b64 s[22:23], s[74:75]
	s_xor_b64 s[48:49], exec, s[22:23]
	s_add_u32 s34, s44, 0x300
	s_addc_u32 s35, s45, 0
	s_mov_b64 s[42:43], exec
	s_or_b64 exec, exec, s[48:49]
	s_and_b64 vcc, exec, s[46:47]
	s_cbranch_vccz .LBB0_275
